# MLA tile loop back edge rotated: the next tile's index and K/V prefetch address arithmetic is done before the loop barrier, so only the three prefetch loads sit between the barrier release and the K f
# speedup vs baseline: 1.0061x; 1.0061x over previous
; #define LAS __attribute__((address_space(3)))
; #define MFMA32(a, b, c) __builtin_amdgcn_mfma_f32_32x32x16_bf16((a), (b), (c), 0, 0, 0)
; __device__ __forceinline__ void mla_unit2(LAS unsigned char* lds, const bf16_t* QB, const bf16_t* KB, const bf16_t* VT, bf16_t* OB, int b, int h, int qb, int wv) {
;     ...
;     for (int t = 0; t < ntiles; ++t) {
;         LAS unsigned char* cur = lds + (t & 1) * M2BUF;
;         { const int tn = (t + 1 < tl) ? t + 1 : tl;
;           ra = *(const u32x4*)(gKA + (size_t)tn * 64 * NQB); rc = *(const u32x4*)(gKC + (size_t)tn * 64 * NQB); rv = *(const u32x4*)(gV + tn * 64); }
;         if (t < nact) {
;             const int k0 = t * 64;
;             f32x16 sa0, sa1, sb0, sb1;
;             { const LAS unsigned char* kp = cur + r * MK_ROW + hh * 16;
; #pragma unroll
;               for (int i = 0; i < 16; ++i) { sa0[i] = 0.f; sa1[i] = 0.f; sb0[i] = 0.f; sb1[i] = 0.f; }
; #pragma unroll
;               for (int hf = 0; hf < 2; ++hf) {
;                   bf16x8 ka[3], kc[3];
; #pragma unroll
;                   for (int s = 0; s < 3; ++s) { ka[s] = *(const LAS bf16x8*)(kp + (3 * hf + s) * 32); kc[s] = *(const LAS bf16x8*)(kp + 32 * MK_ROW + (3 * hf + s) * 32); }
;                   __builtin_amdgcn_sched_barrier(0);
; #pragma unroll
;                   for (int s = 0; s < 3; ++s) { sa0 = MFMA32(ka[s], qa[3 * hf + s], sa0); sa1 = MFMA32(kc[s], qa[3 * hf + s], sa1); sb0 = MFMA32(ka[s], qbf[3 * hf + s], sb0); sb1 = MFMA32(kc[s], qbf[3 * hf + s], sb1); }
;                   __builtin_amdgcn_sched_barrier(0);
;               } }
.LBB0_661:
	s_add_i32 s76, s0, 1
	s_min_u32 s1, s76, s73
	s_mul_i32 s12, s1, 0x18000
	v_lshl_add_u64 v[192:193], v[200:201], 0, s[12:13]
	v_lshl_add_u64 v[194:195], v[202:203], 0, s[12:13]
	s_lshl_b32 s12, s1, 7
	v_lshl_add_u64 v[226:227], v[204:205], 0, s[12:13]
.Lmla_head:
	global_load_dwordx4 v[6:9], v[192:193], off
	s_nop 0
	global_load_dwordx4 v[2:5], v[194:195], off
	s_cmp_gt_i32 s0, s72
	global_load_dwordx4 v[10:13], v[226:227], off
	s_cbranch_scc1 .LBB0_676
	s_bitcmp1_b32 s0, 0
	s_cselect_b32 s0, 0x5800, 0
	s_add_i32 s12, s0, 0
	v_add3_u32 v0, s12, v209, v206
	ds_read_b128 v[80:83], v0
	ds_read_b128 v[226:229], v0 offset:32
	ds_read_b128 v[84:87], v0 offset:6656
	ds_read_b128 v[230:233], v0 offset:64
	ds_read_b128 v[234:237], v0 offset:6688
	ds_read_b128 v[238:241], v0 offset:6720
	s_waitcnt vmcnt(14) lgkmcnt(5)
	v_mfma_f32_32x32x16_bf16 v[128:143], v[80:83], v[144:147], 0
	s_waitcnt lgkmcnt(3)
	v_mfma_f32_32x32x16_bf16 v[112:127], v[84:87], v[144:147], 0
	s_waitcnt vmcnt(5)
	v_mfma_f32_32x32x16_bf16 v[96:111], v[80:83], v[180:183], 0
	v_mfma_f32_32x32x16_bf16 v[80:95], v[84:87], v[180:183], 0
	v_mfma_f32_32x32x16_bf16 v[128:143], v[226:229], v[148:151], v[128:143]
	s_waitcnt lgkmcnt(1)
	v_mfma_f32_32x32x16_bf16 v[112:127], v[234:237], v[148:151], v[112:127]
	v_mfma_f32_32x32x16_bf16 v[96:111], v[226:229], v[156:159], v[96:111]
	v_mfma_f32_32x32x16_bf16 v[80:95], v[234:237], v[156:159], v[80:95]
	v_mfma_f32_32x32x16_bf16 v[128:143], v[230:233], v[152:155], v[128:143]
	s_waitcnt lgkmcnt(0)
	v_mfma_f32_32x32x16_bf16 v[112:127], v[238:241], v[152:155], v[112:127]
	v_mfma_f32_32x32x16_bf16 v[96:111], v[230:233], v[160:163], v[96:111]
	v_mfma_f32_32x32x16_bf16 v[80:95], v[238:241], v[160:163], v[80:95]
	ds_read_b128 v[226:229], v0 offset:96
	ds_read_b128 v[230:233], v0 offset:128
	ds_read_b128 v[234:237], v0 offset:6752
	ds_read_b128 v[238:241], v0 offset:160
	ds_read_b128 v[242:245], v0 offset:6784
	ds_read_b128 v[246:249], v0 offset:6816
	s_waitcnt lgkmcnt(5)
	v_mfma_f32_32x32x16_bf16 v[128:143], v[226:229], v[164:167], v[128:143]
	s_waitcnt lgkmcnt(3)
	v_mfma_f32_32x32x16_bf16 v[112:127], v[234:237], v[164:167], v[112:127]
	v_mfma_f32_32x32x16_bf16 v[96:111], v[226:229], v[172:175], v[96:111]
	v_mfma_f32_32x32x16_bf16 v[80:95], v[234:237], v[172:175], v[80:95]
	v_mfma_f32_32x32x16_bf16 v[128:143], v[230:233], v[168:171], v[128:143]
	s_waitcnt lgkmcnt(1)
	v_mfma_f32_32x32x16_bf16 v[112:127], v[242:245], v[168:171], v[112:127]
	v_mfma_f32_32x32x16_bf16 v[96:111], v[230:233], v[176:179], v[96:111]
	v_mfma_f32_32x32x16_bf16 v[80:95], v[242:245], v[176:179], v[80:95]
	s_waitcnt vmcnt(4)
	v_mfma_f32_32x32x16_bf16 v[128:143], v[238:241], v[184:187], v[128:143]
	s_waitcnt lgkmcnt(0)
	v_mfma_f32_32x32x16_bf16 v[112:127], v[246:249], v[184:187], v[112:127]
	s_waitcnt vmcnt(3)
	v_mfma_f32_32x32x16_bf16 v[96:111], v[238:241], v[188:191], v[96:111]
	v_mfma_f32_32x32x16_bf16 v[80:95], v[246:249], v[188:191], v[80:95]
	s_add_i32 s25, s71, 63
	s_cmp_le_i32 s25, s70
	s_nop 7
	s_cbranch_scc1 .Lmla_nomask
	s_cmp_eq_u32 s100, 0
	s_cbranch_scc1 .Lmla_m663
	s_mov_b32 s100, 0
	s_cmp_lg_u32 s71, 0
	s_cbranch_scc1 .Lmla_m663
	v_mov_b32_e32 v224, 0xff800000
	v_mov_b32_e32 v223, 0xff800000

; #define LAS __attribute__((address_space(3)))
; __device__ __forceinline__ void mla_unit2(LAS unsigned char* lds, const bf16_t* QB, const bf16_t* KB, const bf16_t* VT, bf16_t* OB, int b, int h, int qb, int wv) {
;     ...
;         { const int tn = (t + 1 < tl) ? t + 1 : tl;
;           ra = *(const u32x4*)(gKA + (size_t)tn * 64 * NQB); rc = *(const u32x4*)(gKC + (size_t)tn * 64 * NQB); rv = *(const u32x4*)(gV + tn * 64); }
;     ...
;         { LAS unsigned char* nxt = lds + ((t + 1) & 1) * M2BUF;
;           *(LAS u32x4*)(nxt + lKA) = ra; *(LAS u32x4*)(nxt + lKC) = rc; *(LAS u32x4*)(nxt + lV) = rv; }
;         __syncthreads();
.LBB0_676:
	s_bitcmp1_b32 s76, 0
	s_cselect_b32 s0, 0x5800, 0
	s_add_i32 s0, s0, 0
	v_add_u32_e32 v0, s0, v197
	s_waitcnt vmcnt(2)
	ds_write_b128 v0, v[6:9]
	v_add_u32_e32 v0, s0, v207
	s_add_i32 s71, s71, 64
	s_waitcnt vmcnt(1)
	ds_write_b128 v0, v[2:5]
	v_add_u32_e32 v0, s0, v208
	s_waitcnt vmcnt(0)
	ds_write_b128 v0, v[10:13] offset:13312
	s_mov_b32 s0, s76
	s_add_i32 s76, s0, 1
	s_min_u32 s1, s76, s73
	s_mul_i32 s12, s1, 0x18000
	v_lshl_add_u64 v[192:193], v[200:201], 0, s[12:13]
	v_lshl_add_u64 v[194:195], v[202:203], 0, s[12:13]
	s_lshl_b32 s12, s1, 7
	v_lshl_add_u64 v[226:227], v[204:205], 0, s[12:13]
	s_cmp_lg_u32 s75, s71
	s_waitcnt lgkmcnt(0)
	s_barrier
	s_cbranch_scc0 .LBB0_659
	s_branch .Lmla_head
